# v24 + pre-norm loop prefetches the next row (4 loads in flight) while the current row is reduced and stored
# baseline (speedup 1.0000x reference)
; DI unsigned pk2(float lo, float hi) { f32x2 v = {lo, hi}; bf16x2_t b = __builtin_convertvector(v, bf16x2_t); return __builtin_bit_cast(unsigned, b); }
; DI void norm_phase(Frame& F, const float* srcL, const float* srcC, const float* g, const float* modl, int sub) {
;     ...
;     for (int row = gw * RPW; row < gw * RPW + RPW; ++row) {
;         const int bi = row < TL ? (row >> 12) : 16;
;         if (bi != cur_bi) { cur_bi = bi; const float* mp = modl + (size_t)bi * MODW + sub * 3072;
; #pragma unroll
;             for (int j = 0; j < 4; ++j) { const int k = (F.lane + 64 * j) * 4; const f32x4 gg = *(const f32x4*)(g + k), sc = *(const f32x4*)(mp + 1024 + k); sh[j] = *(const f32x4*)(mp + k); gs[j] = gg * (sc + 1.0f); } }
;         const float* src = row < TL ? srcL + (size_t)row * DM : srcC + (size_t)(row - TL) * DM;
;         f32x4 v[4]; float ss = 0.f;
; #pragma unroll
;         for (int j = 0; j < 4; ++j) { v[j] = __builtin_nontemporal_load((const f32x4*)(src + (F.lane + 64 * j) * 4)); ss += (v[j][0] * v[j][0] + v[j][1] * v[j][1]) + (v[j][2] * v[j][2] + v[j][3] * v[j][3]); }
;         const float rstd = rsqrtf(wave_sum(ss) * (1.0f / DM) + EPS);
;         bf16_t* hp = H + (size_t)row * DM;
; #pragma unroll
;         for (int j = 0; j < 4; ++j) { const f32x4 o = v[j] * rstd * gs[j] + sh[j]; u32x2 w; w.x = pk2(o[0], o[1]); w.y = pk2(o[2], o[3]); *(u32x2*)(hp + (F.lane + 64 * j) * 4) = w; }
;     }
.Lnp_nosplit:
	s_mov_b32 s99, 0
	s_branch .LBB0_527
.LBB0_526:
	s_cmp_eq_u32 s99, 1
	s_cbranch_scc1 .Lnp_pf_use
	global_load_dwordx4 v[48:51], v0, s[62:63] nt
	global_load_dwordx4 v[52:55], v0, s[62:63] offset:1024 nt
	global_load_dwordx4 v[56:59], v0, s[62:63] offset:3072 nt
	global_load_dwordx4 v[60:63], v0, s[62:63] offset:2048 nt
	s_branch .Lnp_pf_next
.Lnp_pf_use:
	s_waitcnt vmcnt(4)
	v_mov_b64_e32 v[48:49], v[80:81]
	v_mov_b64_e32 v[50:51], v[82:83]
	v_mov_b64_e32 v[52:53], v[84:85]
	v_mov_b64_e32 v[54:55], v[86:87]
	v_mov_b64_e32 v[56:57], v[88:89]
	v_mov_b64_e32 v[58:59], v[90:91]
	v_mov_b64_e32 v[60:61], v[92:93]
	v_mov_b64_e32 v[62:63], v[94:95]
.Lnp_pf_next:
	s_add_i32 s30, s16, 1
	s_cmp_ge_i32 s30, s11
	s_cselect_b32 s30, 0, 1
	s_add_u32 s18, s4, s30
	s_cmp_lt_u32 s18, 0x10000
	s_cbranch_scc0 .Lnp_pf_ctx
	s_lshl_b32 s30, s30, 12
	s_add_u32 s18, s6, s30
	s_addc_u32 s19, s7, 0
	s_branch .Lnp_pf_issue
.Lnp_pf_ctx:
	s_sub_u32 s18, s18, 0x10000
	s_lshl_b32 s18, s18, 12
	s_add_u32 s18, s56, s18
	s_addc_u32 s19, s57, 0
.Lnp_pf_issue:
	global_load_dwordx4 v[80:83], v0, s[18:19] nt
	global_load_dwordx4 v[84:87], v0, s[18:19] offset:1024 nt
	global_load_dwordx4 v[88:91], v0, s[18:19] offset:3072 nt
	global_load_dwordx4 v[92:95], v0, s[18:19] offset:2048 nt
	s_mov_b32 s99, 1
	s_lshl_b64 s[8:9], s[8:9], 11
	s_add_u32 s4, s4, 1
	s_addc_u32 s5, s5, 0
	s_add_u32 s6, s6, 0x1000
	s_addc_u32 s7, s7, 0
	s_add_i32 s16, s16, 1
	s_cmp_ge_i32 s16, s11
	s_waitcnt vmcnt(4)
	v_pk_mul_f32 v[64:65], v[50:51], v[50:51]
	v_pk_mul_f32 v[66:67], v[48:49], v[48:49]
	v_pk_mul_f32 v[68:69], v[54:55], v[54:55]
	v_pk_mul_f32 v[70:71], v[52:53], v[52:53]
	v_pk_mov_b32 v[74:75], v[66:67], v[64:65] op_sel:[1,0]
	v_mov_b32_e32 v67, v65
	v_pk_mov_b32 v[64:65], v[70:71], v[68:69] op_sel:[1,0]
	v_mov_b32_e32 v71, v69
	v_mul_f32_e32 v0, v61, v61
	v_mul_f32_e32 v72, v63, v63
	v_pk_add_f32 v[66:67], v[74:75], v[66:67]
	v_pk_add_f32 v[64:65], v[64:65], v[70:71]
	v_mul_f32_e32 v76, v56, v56
	v_mul_f32_e32 v77, v57, v57
	v_mul_f32_e32 v78, v58, v58
	v_mul_f32_e32 v79, v59, v59
	v_pk_fma_f32 v[68:69], v[60:61], v[60:61], v[0:1] op_sel_hi:[1,1,0]
	v_pk_fma_f32 v[72:73], v[62:63], v[62:63], v[72:73] op_sel_hi:[1,1,0]
	v_pk_add_f32 v[66:67], v[66:67], v[66:67] op_sel:[0,1] op_sel_hi:[1,0]
	v_pk_add_f32 v[64:65], v[64:65], v[64:65] op_sel:[0,1] op_sel_hi:[1,0]
	v_mov_b32_e32 v69, v78
	v_mov_b32_e32 v73, v79
	v_mov_b32_e32 v67, v76
	v_mov_b32_e32 v65, v77
	v_pk_add_f32 v[68:69], v[68:69], v[72:73]
	v_pk_add_f32 v[64:65], v[66:67], v[64:65]
	s_nop 0
	v_pk_add_f32 v[64:65], v[64:65], v[68:69]
	s_nop 0
	v_add_f32_e32 v0, v64, v65
	ds_bpermute_b32 v64, v35, v0
	s_waitcnt lgkmcnt(0)
	v_add_f32_e32 v0, v0, v64
	ds_bpermute_b32 v64, v40, v0
	s_waitcnt lgkmcnt(0)
	v_add_f32_e32 v0, v0, v64
	ds_bpermute_b32 v64, v41, v0
	s_waitcnt lgkmcnt(0)
	v_add_f32_e32 v0, v0, v64
	ds_bpermute_b32 v64, v42, v0
	s_waitcnt lgkmcnt(0)
	v_add_f32_e32 v0, v0, v64
	ds_bpermute_b32 v64, v43, v0
	s_waitcnt lgkmcnt(0)
	v_add_f32_e32 v0, v0, v64
	ds_bpermute_b32 v66, v44, v0
	v_lshl_add_u64 v[64:65], v[38:39], 0, s[8:9]
	s_waitcnt lgkmcnt(0)
	v_add_f32_e32 v0, v0, v66
	v_fmamk_f32 v0, v0, 0x3a800000, v162
	v_mul_f32_e32 v66, 0x4b800000, v0
	v_cmp_gt_f32_e32 vcc, s27, v0
	s_nop 1
	v_cndmask_b32_e32 v0, v0, v66, vcc
	v_rsq_f32_e32 v0, v0
	s_nop 0
	v_mul_f32_e32 v66, 0x45800000, v0
	v_cndmask_b32_e32 v0, v0, v66, vcc
	v_pk_mul_f32 v[48:49], v[48:49], v[0:1] op_sel_hi:[1,0]
	v_pk_mul_f32 v[50:51], v[50:51], v[0:1] op_sel_hi:[1,0]
	v_pk_mul_f32 v[52:53], v[52:53], v[0:1] op_sel_hi:[1,0]
	v_pk_mul_f32 v[54:55], v[54:55], v[0:1] op_sel_hi:[1,0]
	v_pk_mul_f32 v[60:61], v[60:61], v[0:1] op_sel_hi:[1,0]
	v_pk_mul_f32 v[62:63], v[62:63], v[0:1] op_sel_hi:[1,0]
	v_pk_mul_f32 v[56:57], v[56:57], v[0:1] op_sel_hi:[1,0]
	v_pk_mul_f32 v[58:59], v[58:59], v[0:1] op_sel_hi:[1,0]
	v_pk_fma_f32 v[50:51], v[4:5], v[50:51], v[32:33]
	v_pk_fma_f32 v[48:49], v[2:3], v[48:49], v[30:31]
	v_pk_fma_f32 v[54:55], v[8:9], v[54:55], v[24:25]
	v_pk_fma_f32 v[52:53], v[6:7], v[52:53], v[22:23]
	v_pk_fma_f32 v[62:63], v[12:13], v[62:63], v[20:21]
	v_pk_fma_f32 v[60:61], v[10:11], v[60:61], v[18:19]
	v_pk_fma_f32 v[58:59], v[16:17], v[58:59], v[28:29]
	v_pk_fma_f32 v[56:57], v[14:15], v[56:57], v[26:27]
	v_cvt_pk_bf16_f32 v48, v48, v49
	v_cvt_pk_bf16_f32 v49, v50, v51
	v_cvt_pk_bf16_f32 v50, v52, v53
	v_cvt_pk_bf16_f32 v51, v54, v55
	v_cvt_pk_bf16_f32 v52, v60, v61
	v_cvt_pk_bf16_f32 v53, v62, v63
	v_cvt_pk_bf16_f32 v54, v56, v57
	v_cvt_pk_bf16_f32 v55, v58, v59
	global_store_dwordx2 v[64:65], v[48:49], off
	global_store_dwordx2 v[64:65], v[50:51], off offset:512
	global_store_dwordx2 v[64:65], v[52:53], off offset:1024
	global_store_dwordx2 v[64:65], v[54:55], off offset:1536
	s_cbranch_scc1 .LBB0_531

; DI void norm_phase(Frame& F, const float* srcL, const float* srcC, const float* g, const float* modl, int sub) {
;     const int gw = F.vcu * 8 + F.wave; constexpr int RPW = TT / 2048;
;     bf16_t* H = WSP(bf16_t, WS_H);
;     int cur_bi = -1; f32x4 gs[4], sh[4];
;     for (int row = gw * RPW; row < gw * RPW + RPW; ++row) {
;         const int bi = row < TL ? (row >> 12) : 16;
;         if (bi != cur_bi) { cur_bi = bi; const float* mp = modl + (size_t)bi * MODW + sub * 3072;
.Lnp_wdone_b:
	s_mov_b64 exec, s[18:19]
	s_barrier
	s_lshl_b32 s8, s12, 3
	s_add_u32 s8, s8, s50
	s_lshl_b32 s8, s8, 1
	s_add_u32 s4, s8, 0x10000
	s_add_u32 s11, s4, 1
	s_mov_b32 s5, 0
	s_sub_u32 s16, s4, 1
	s_mov_b32 s99, 0
	s_branch .LBB0_527
